# v47 + halo fix-up loop: all eight conv weight/bias loads of both column halves issued together (new VGPRs v64-v85), counted vmcnt 7/6/4
# speedup vs baseline: 1.0124x; 1.0124x over previous
.LBB0_1097:
	s_or_b64 exec, exec, s[2:3]
	v_lshlrev_b64 v[50:51], 2, v[38:39]
	v_lshl_add_u64 v[34:35], s[4:5], 0, v[50:51]
	v_lshl_add_u64 v[42:43], s[10:11], 0, v[50:51]
	v_lshl_add_u64 v[84:85], s[4:5], 0, v[50:51]
	global_load_dwordx4 v[34:37], v[34:35], off
	s_waitcnt vmcnt(4)
	v_lshlrev_b32_e32 v46, 16, v18
	global_load_dwordx4 v[30:33], v[42:43], off
	v_and_b32_e32 v47, 0xffff0000, v18
	v_lshlrev_b32_e32 v18, 16, v19
	v_and_b32_e32 v19, 0xffff0000, v19
	v_lshl_add_u64 v[40:41], s[12:13], 0, v[50:51]
	s_waitcnt vmcnt(2)
	v_lshlrev_b32_e32 v44, 16, v22
	v_and_b32_e32 v45, 0xffff0000, v22
	v_lshlrev_b32_e32 v22, 16, v23
	v_and_b32_e32 v23, 0xffff0000, v23
	v_lshl_add_u64 v[50:51], s[16:17], 0, v[50:51]
	global_load_dwordx4 v[26:29], v[40:41], off
	global_load_dwordx4 v[64:67], v[50:51], off
	global_load_dwordx4 v[68:71], v[40:41], off offset:16
	global_load_dwordx4 v[72:75], v[42:43], off offset:16
	global_load_dwordx4 v[76:79], v[84:85], off offset:16
	global_load_dwordx4 v[80:83], v[50:51], off offset:16
	v_lshlrev_b32_e32 v58, 16, v14
	v_and_b32_e32 v59, 0xffff0000, v14
	v_lshlrev_b32_e32 v14, 16, v15
	v_and_b32_e32 v15, 0xffff0000, v15
	s_waitcnt vmcnt(7)
	v_pk_mul_f32 v[52:53], v[36:37], v[18:19]
	v_pk_mul_f32 v[54:55], v[34:35], v[46:47]
	s_waitcnt vmcnt(6)
	v_pk_fma_f32 v[56:57], v[32:33], v[22:23], v[52:53]
	v_pk_fma_f32 v[54:55], v[30:31], v[44:45], v[54:55]
	v_pk_mul_f32 v[22:23], v[36:37], v[22:23]
	v_pk_mul_f32 v[34:35], v[34:35], v[44:45]
	v_lshlrev_b32_e32 v36, 16, v20
	v_and_b32_e32 v37, 0xffff0000, v20
	s_waitcnt vmcnt(4)
	v_pk_fma_f32 v[54:55], v[64:65], v[58:59], v[54:55]
	s_nop 0
	v_pk_add_f32 v[54:55], v[26:27], v[54:55]
	v_pk_fma_f32 v[14:15], v[66:67], v[14:15], v[56:57]
	v_mul_f32_e32 v49, 0x3dd2d3e8, v54
	v_fma_f32 v49, -v54, v49, s59
	v_mul_f32_e32 v49, v54, v49
	v_exp_f32_e32 v49, v49
	v_pk_add_f32 v[14:15], v[28:29], v[14:15]
	v_add_f32_e32 v49, 1.0, v49
	v_rcp_f32_e32 v56, v49
	v_mul_f32_e32 v49, 0x3dd2d3e8, v55
	v_fma_f32 v49, -v55, v49, s59
	v_mul_f32_e32 v49, v55, v49
	v_exp_f32_e32 v49, v49
	s_nop 0
	v_add_f32_e32 v49, 1.0, v49
	v_rcp_f32_e32 v57, v49
	v_mul_f32_e32 v49, 0x3dd2d3e8, v14
	v_fma_f32 v49, -v14, v49, s59
	v_mul_f32_e32 v49, v14, v49
	v_exp_f32_e32 v49, v49
	v_pk_mul_f32 v[54:55], v[54:55], v[56:57]
	v_lshlrev_b32_e32 v56, 16, v6
	v_and_b32_e32 v57, 0xffff0000, v6
	v_add_f32_e32 v49, 1.0, v49
	v_rcp_f32_e32 v58, v49
	v_mul_f32_e32 v49, 0x3dd2d3e8, v15
	v_fma_f32 v49, -v15, v49, s59
	v_mul_f32_e32 v49, v15, v49
	v_exp_f32_e32 v49, v49
	v_lshlrev_b32_e32 v6, 16, v7
	v_and_b32_e32 v7, 0xffff0000, v7
	v_add_f32_e32 v49, 1.0, v49
	v_rcp_f32_e32 v59, v49
	s_nop 0
	v_pk_mul_f32 v[14:15], v[14:15], v[58:59]
	s_nop 0
	v_pk_mul_f32 v[14:15], v[14:15], v[6:7]
	v_pk_mul_f32 v[6:7], v[54:55], v[56:57]
	v_lshlrev_b32_e32 v54, 16, v10
	v_and_b32_e32 v55, 0xffff0000, v10
	v_lshlrev_b32_e32 v10, 16, v11
	v_and_b32_e32 v11, 0xffff0000, v11
	v_pk_fma_f32 v[10:11], v[32:33], v[10:11], v[22:23]
	v_pk_fma_f32 v[22:23], v[30:31], v[54:55], v[34:35]
	v_pk_fma_f32 v[10:11], v[66:67], v[18:19], v[10:11]
	v_pk_fma_f32 v[22:23], v[64:65], v[46:47], v[22:23]
	v_pk_add_f32 v[18:19], v[28:29], v[10:11]
	v_pk_add_f32 v[10:11], v[26:27], v[22:23]
	v_mul_f32_e32 v26, 0x3dd2d3e8, v18
	v_mul_f32_e32 v22, 0x3dd2d3e8, v10
	v_mul_f32_e32 v23, 0x3dd2d3e8, v11
	v_mul_f32_e32 v27, 0x3dd2d3e8, v19
	v_fma_f32 v22, -v10, v22, s59
	v_fma_f32 v23, -v11, v23, s59
	v_fma_f32 v26, -v18, v26, s59
	v_fma_f32 v27, -v19, v27, s59
	v_mul_f32_e32 v22, v10, v22
	v_mul_f32_e32 v23, v11, v23
	v_mul_f32_e32 v26, v18, v26
	v_mul_f32_e32 v27, v19, v27
	v_exp_f32_e32 v22, v22
	v_exp_f32_e32 v23, v23
	v_exp_f32_e32 v26, v26
	v_exp_f32_e32 v27, v27
	v_add_f32_e32 v22, 1.0, v22
	v_add_f32_e32 v23, 1.0, v23
	v_add_f32_e32 v26, 1.0, v26
	v_add_f32_e32 v27, 1.0, v27
	v_rcp_f32_e32 v22, v22
	v_rcp_f32_e32 v23, v23
	v_rcp_f32_e32 v26, v26
	v_rcp_f32_e32 v27, v27
	v_lshlrev_b32_e32 v34, 16, v25
	v_pk_mul_f32 v[10:11], v[10:11], v[22:23]
	v_lshlrev_b32_e32 v22, 16, v2
	v_pk_mul_f32 v[18:19], v[18:19], v[26:27]
	v_and_b32_e32 v23, 0xffff0000, v2
	v_lshlrev_b32_e32 v2, 16, v3
	v_and_b32_e32 v3, 0xffff0000, v3
	v_pk_mul_f32 v[18:19], v[18:19], v[2:3]
	v_pk_mul_f32 v[2:3], v[10:11], v[22:23]
	v_or_b32_e32 v10, 4, v38
	v_ashrrev_i32_e32 v11, 31, v10
	v_lshlrev_b64 v[10:11], 2, v[10:11]
	v_cvt_pk_bf16_f32 v2, v2, v3
	v_cvt_pk_bf16_f32 v3, v18, v19
	v_lshl_add_u64 v[18:19], s[4:5], 0, v[10:11]
	v_cvt_pk_bf16_f32 v6, v6, v7
	v_cvt_pk_bf16_f32 v7, v14, v15
	v_lshlrev_b32_e32 v14, 16, v24
	v_and_b32_e32 v15, 0xffff0000, v24
	v_and_b32_e32 v35, 0xffff0000, v25
	v_lshlrev_b32_e32 v40, 16, v21
	v_and_b32_e32 v41, 0xffff0000, v21
	v_lshl_add_u64 v[10:11], s[16:17], 0, v[10:11]
	s_waitcnt vmcnt(0)
	v_pk_mul_f32 v[18:19], v[78:79], v[40:41]
	v_pk_mul_f32 v[20:21], v[76:77], v[36:37]
	v_pk_fma_f32 v[44:45], v[74:75], v[34:35], v[18:19]
	v_pk_fma_f32 v[42:43], v[72:73], v[14:15], v[20:21]
	v_lshlrev_b32_e32 v10, 16, v16
	v_and_b32_e32 v11, 0xffff0000, v16
	v_lshlrev_b32_e32 v16, 16, v17
	v_and_b32_e32 v17, 0xffff0000, v17
	v_pk_mul_f32 v[24:25], v[78:79], v[34:35]
	v_pk_mul_f32 v[14:15], v[76:77], v[14:15]
	s_waitcnt vmcnt(0)
	v_pk_fma_f32 v[16:17], v[82:83], v[16:17], v[44:45]
	v_pk_fma_f32 v[10:11], v[80:81], v[10:11], v[42:43]
	v_pk_add_f32 v[16:17], v[70:71], v[16:17]
	v_pk_add_f32 v[10:11], v[68:69], v[10:11]
	v_mul_f32_e32 v44, 0x3dd2d3e8, v16
	v_mul_f32_e32 v45, 0x3dd2d3e8, v17
	v_mul_f32_e32 v42, 0x3dd2d3e8, v10
	v_mul_f32_e32 v43, 0x3dd2d3e8, v11
	v_fma_f32 v44, -v16, v44, s59
	v_fma_f32 v45, -v17, v45, s59
	v_fma_f32 v42, -v10, v42, s59
	v_fma_f32 v43, -v11, v43, s59
	v_mul_f32_e32 v44, v16, v44
	v_mul_f32_e32 v45, v17, v45
	v_mul_f32_e32 v42, v10, v42
	v_mul_f32_e32 v43, v11, v43
	v_exp_f32_e32 v44, v44
	v_exp_f32_e32 v45, v45
	v_exp_f32_e32 v42, v42
	v_exp_f32_e32 v43, v43
	v_add_f32_e32 v44, 1.0, v44
	v_add_f32_e32 v45, 1.0, v45
	v_add_f32_e32 v42, 1.0, v42
	v_add_f32_e32 v43, 1.0, v43
	v_rcp_f32_e32 v44, v44
	v_rcp_f32_e32 v45, v45
	v_rcp_f32_e32 v42, v42
	v_rcp_f32_e32 v43, v43
	v_pk_mul_f32 v[16:17], v[16:17], v[44:45]
	v_lshlrev_b32_e32 v44, 16, v8
	v_and_b32_e32 v45, 0xffff0000, v8
	v_lshlrev_b32_e32 v8, 16, v9
	v_and_b32_e32 v9, 0xffff0000, v9
	v_pk_mul_f32 v[42:43], v[10:11], v[42:43]
	v_pk_mul_f32 v[10:11], v[16:17], v[8:9]
	v_lshlrev_b32_e32 v16, 16, v12
	v_and_b32_e32 v17, 0xffff0000, v12
	v_lshlrev_b32_e32 v12, 16, v13
	v_and_b32_e32 v13, 0xffff0000, v13
	v_pk_fma_f32 v[14:15], v[72:73], v[16:17], v[14:15]
	v_pk_fma_f32 v[12:13], v[74:75], v[12:13], v[24:25]
	v_pk_fma_f32 v[16:17], v[80:81], v[36:37], v[14:15]
	v_pk_fma_f32 v[12:13], v[82:83], v[40:41], v[12:13]
	v_pk_mul_f32 v[8:9], v[42:43], v[44:45]
	v_pk_add_f32 v[14:15], v[70:71], v[12:13]
	v_pk_add_f32 v[12:13], v[68:69], v[16:17]
	v_mul_f32_e32 v18, 0x3dd2d3e8, v14
	v_mul_f32_e32 v16, 0x3dd2d3e8, v12
	v_mul_f32_e32 v17, 0x3dd2d3e8, v13
	v_mul_f32_e32 v19, 0x3dd2d3e8, v15
	v_fma_f32 v16, -v12, v16, s59
	v_fma_f32 v17, -v13, v17, s59
	v_fma_f32 v18, -v14, v18, s59
	v_fma_f32 v19, -v15, v19, s59
	v_mul_f32_e32 v16, v12, v16
	v_mul_f32_e32 v17, v13, v17
	v_mul_f32_e32 v18, v14, v18
	v_mul_f32_e32 v19, v15, v19
	v_exp_f32_e32 v16, v16
	v_exp_f32_e32 v17, v17
	v_exp_f32_e32 v18, v18
	v_exp_f32_e32 v19, v19
	v_add_f32_e32 v16, 1.0, v16
	v_add_f32_e32 v17, 1.0, v17
	v_add_f32_e32 v18, 1.0, v18
	v_add_f32_e32 v19, 1.0, v19
	v_rcp_f32_e32 v16, v16
	v_rcp_f32_e32 v17, v17
	v_rcp_f32_e32 v18, v18
	v_rcp_f32_e32 v19, v19
	v_pk_mul_f32 v[12:13], v[12:13], v[16:17]
	v_lshlrev_b32_e32 v16, 16, v4
	v_pk_mul_f32 v[14:15], v[14:15], v[18:19]
	v_and_b32_e32 v17, 0xffff0000, v4
	v_lshlrev_b32_e32 v4, 16, v5
	v_and_b32_e32 v5, 0xffff0000, v5
	v_pk_mul_f32 v[14:15], v[14:15], v[4:5]
	v_pk_mul_f32 v[4:5], v[12:13], v[16:17]
	v_lshlrev_b32_e32 v16, 6, v48
	v_cvt_pk_bf16_f32 v4, v4, v5
	v_cvt_pk_bf16_f32 v5, v14, v15
	v_cvt_pk_bf16_f32 v8, v8, v9
	v_cvt_pk_bf16_f32 v9, v10, v11
	v_mov_b64_e32 v[10:11], s[68:69]
	v_mad_i64_i32 v[12:13], s[2:3], v16, s24, v[10:11]
	v_lshlrev_b64 v[14:15], 1, v[38:39]
	v_lshl_add_u64 v[12:13], v[12:13], 0, v[14:15]
	global_store_dwordx4 v[12:13], v[2:5], off
	s_nop 1
	v_or_b32_e32 v2, 1, v16
	v_mad_i64_i32 v[2:3], s[2:3], v2, s24, v[10:11]
	v_lshl_add_u64 v[2:3], v[2:3], 0, v[14:15]
	s_mov_b32 s2, 0xafff
	global_store_dwordx4 v[2:3], v[6:9], off
	v_add_u32_e32 v2, 0x20000, v0
	v_cmp_lt_i32_e32 vcc, s2, v0
	s_or_b64 s[6:7], vcc, s[6:7]
	v_mov_b32_e32 v0, v2
	s_andn2_b64 exec, exec, s[6:7]
	s_cbranch_execz .LBB0_1100
